# v32 + P0 x-rmsnorm: loop-invariant gain vector loaded once before the row loop (removes 7 reload+vmcnt(0) round trips per row)
# speedup vs baseline: 1.0149x; 1.0149x over previous
.LBB0_83:
	s_cmpk_gt_i32 s26, 0x3fff
	s_cbranch_scc1 .LBB0_86
	v_mbcnt_lo_u32_b32 v2, -1, 0
	v_mbcnt_hi_u32_b32 v2, -1, v2
	v_and_b32_e32 v3, 64, v2
	v_add_u32_e32 v3, 64, v3
	v_xor_b32_e32 v4, 1, v2
	v_cmp_lt_i32_e32 vcc, v4, v3
	s_ashr_i32 s27, s26, 31
	s_lshl_b64 s[6:7], s[26:27], 12
	v_cndmask_b32_e32 v4, v2, v4, vcc
	v_lshlrev_b32_e32 v33, 2, v4
	v_xor_b32_e32 v4, 2, v2
	v_cmp_lt_i32_e32 vcc, v4, v3
	s_add_u32 s6, s8, s6
	s_addc_u32 s7, s9, s7
	v_cndmask_b32_e32 v4, v2, v4, vcc
	v_lshlrev_b32_e32 v34, 2, v4
	v_xor_b32_e32 v4, 4, v2
	v_cmp_lt_i32_e32 vcc, v4, v3
	s_ashr_i32 s35, s34, 31
	s_mov_b64 s[0:1], 0x1000
	v_cndmask_b32_e32 v4, v2, v4, vcc
	v_lshlrev_b32_e32 v35, 2, v4
	v_xor_b32_e32 v4, 8, v2
	v_cmp_lt_i32_e32 vcc, v4, v3
	s_lshl_b64 s[10:11], s[26:27], 13
	v_mov_b32_e32 v39, 0x358637bd
	v_cndmask_b32_e32 v4, v2, v4, vcc
	v_lshlrev_b32_e32 v36, 2, v4
	v_xor_b32_e32 v4, 16, v2
	v_cmp_lt_i32_e32 vcc, v4, v3
	s_mov_b32 s12, 0xf800000
	v_mov_b32_e32 v40, 0x260
	v_cndmask_b32_e32 v4, v2, v4, vcc
	v_lshlrev_b32_e32 v37, 2, v4
	v_xor_b32_e32 v4, 32, v2
	v_cmp_lt_i32_e32 vcc, v4, v3
	v_mov_b32_e32 v3, 0
	v_mov_b32_e32 v5, v3
	v_cndmask_b32_e32 v2, v2, v4, vcc
	v_lshlrev_b32_e32 v4, 3, v208
	v_lshlrev_b32_e32 v38, 2, v2
	v_lshlrev_b32_e32 v2, 4, v208
	v_lshl_add_u64 v[4:5], s[6:7], 0, v[4:5]
	s_mov_b64 s[6:7], 0x8000000
	v_lshl_add_u64 v[18:19], s[58:59], 0, v[2:3]
	v_lshl_add_u64 v[28:29], v[4:5], 0, s[6:7]
	s_lshl_b64 s[6:7], s[34:35], 12
	v_lshl_add_u64 v[20:21], v[18:19], 0, s[0:1]
	s_mov_b64 s[0:1], 0x1400
	s_add_u32 s10, s52, s10
	v_lshl_add_u64 v[22:23], v[18:19], 0, s[0:1]
	s_mov_b64 s[0:1], 0x1800
	s_addc_u32 s11, s53, s11
	v_lshl_add_u64 v[24:25], v[18:19], 0, s[0:1]
	s_mov_b64 s[0:1], 0x1c00
	v_lshl_add_u64 v[2:3], s[10:11], 0, v[2:3]
	v_lshl_add_u64 v[26:27], v[18:19], 0, s[0:1]
	v_lshl_add_u64 v[30:31], v[2:3], 0, s[0:1]
	s_lshl_b64 s[10:11], s[34:35], 13
	s_movk_i32 s13, 0x7fff
	v_mov_b32_e32 v41, 1
	s_mov_b32 s14, s26
	global_load_dwordx4 v[140:143], v[18:19], off
	global_load_dwordx4 v[144:147], v[18:19], off offset:1024
	global_load_dwordx4 v[148:151], v[18:19], off offset:2048
	global_load_dwordx4 v[152:155], v[18:19], off offset:3072
	global_load_dwordx4 v[156:159], v[20:21], off
	global_load_dwordx4 v[160:163], v[22:23], off
	global_load_dwordx4 v[164:167], v[24:25], off
	global_load_dwordx4 v[168:171], v[26:27], off
	s_waitcnt vmcnt(0)
.LBB0_85:
	global_load_dwordx4 v[14:17], v[30:31], off offset:-3072
	global_load_dwordx4 v[10:13], v[30:31], off offset:-2048
	global_load_dwordx4 v[2:5], v[30:31], off
	global_load_dwordx4 v[6:9], v[30:31], off offset:-1024
	v_add_co_u32_e32 v62, vcc, 0xfffff000, v30
	s_add_i32 s14, s14, s34
	s_nop 0
	v_addc_co_u32_e32 v63, vcc, -1, v31, vcc
	global_load_dwordx4 v[46:49], v[62:63], off offset:-3072
	global_load_dwordx4 v[50:53], v[62:63], off offset:-2048
	global_load_dwordx4 v[54:57], v[62:63], off offset:-1024
	global_load_dwordx4 v[58:61], v[30:31], off offset:-4096
	s_cmpk_gt_i32 s14, 0x3fff
	v_lshl_add_u64 v[30:31], v[30:31], 0, s[10:11]
	s_waitcnt vmcnt(0)
	v_mov_b64_e32 v[42:43], v[140:141]
	v_mov_b64_e32 v[44:45], v[142:143]
	v_mul_f32_e32 v84, v14, v14
	v_pk_mul_f32 v[62:63], v[12:13], v[12:13]
	v_pk_mul_f32 v[64:65], v[10:11], v[10:11]
	v_mul_f32_e32 v32, v7, v7
	v_mul_f32_e32 v66, v9, v9
	v_mul_f32_e32 v83, v4, v4
	v_mul_f32_e32 v90, v5, v5
	v_mov_b32_e32 v68, v42
	v_mov_b32_e32 v69, v44
	v_mov_b32_e32 v44, v43
	v_pk_mov_b32 v[42:43], v[64:65], v[62:63] op_sel:[1,0]
	v_mov_b32_e32 v65, v63
	v_pk_fma_f32 v[62:63], v[6:7], v[6:7], v[32:33] op_sel_hi:[1,1,0]
	v_pk_fma_f32 v[66:67], v[8:9], v[8:9], v[66:67] op_sel_hi:[1,1,0]
	v_mov_b32_e32 v72, v47
	v_mov_b32_e32 v73, v51
	v_mov_b32_e32 v76, v49
	v_mov_b32_e32 v77, v53
	v_mov_b32_e32 v70, v46
	v_mov_b32_e32 v71, v50
	v_mov_b32_e32 v74, v48
	v_mov_b32_e32 v75, v52
	v_pk_mul_f32 v[78:79], v[56:57], v[56:57]
	v_pk_mul_f32 v[80:81], v[54:55], v[54:55]
	v_pk_add_f32 v[42:43], v[42:43], v[64:65]
	v_mov_b32_e32 v63, v83
	v_mov_b32_e32 v67, v90
	v_mov_b32_e32 v64, v46
	v_mov_b32_e32 v65, v48
	v_mov_b32_e32 v48, v47
	v_mov_b32_e32 v46, v50
	v_mov_b32_e32 v47, v52
	v_mov_b32_e32 v52, v51
	v_pk_mul_f32 v[50:51], v[72:73], v[72:73]
	v_pk_mul_f32 v[72:73], v[76:77], v[76:77]
	v_pk_mov_b32 v[76:77], v[80:81], v[78:79] op_sel:[1,0]
	v_mov_b32_e32 v81, v79
	v_pk_add_f32 v[62:63], v[62:63], v[66:67]
	v_pk_fma_f32 v[50:51], v[70:71], v[70:71], v[50:51]
	v_pk_fma_f32 v[66:67], v[74:75], v[74:75], v[72:73]
	v_mul_f32_e32 v32, v59, v59
	v_mul_f32_e32 v82, v61, v61
	v_pk_add_f32 v[70:71], v[76:77], v[80:81]
	v_pk_add_f32 v[50:51], v[50:51], v[66:67]
	v_mul_f32_e32 v85, v15, v15
	v_mul_f32_e32 v86, v16, v16
	v_mul_f32_e32 v87, v17, v17
	v_pk_fma_f32 v[78:79], v[58:59], v[58:59], v[32:33] op_sel_hi:[1,1,0]
	v_pk_fma_f32 v[82:83], v[60:61], v[60:61], v[82:83] op_sel_hi:[1,1,0]
	v_pk_add_f32 v[66:67], v[70:71], v[70:71] op_sel:[0,1] op_sel_hi:[1,0]
	v_pk_add_f32 v[50:51], v[50:51], v[50:51] op_sel:[0,1] op_sel_hi:[1,0]
	v_mov_b32_e32 v79, v86
	v_mov_b32_e32 v83, v87
	v_mov_b32_e32 v67, v85
	v_mov_b32_e32 v51, v84
	v_pk_add_f32 v[70:71], v[78:79], v[82:83]
	v_pk_add_f32 v[50:51], v[50:51], v[66:67]
	v_mul_f32_e32 v88, v2, v2
	v_pk_add_f32 v[50:51], v[50:51], v[70:71]
	v_mul_f32_e32 v89, v3, v3
	v_pk_add_f32 v[42:43], v[42:43], v[42:43] op_sel:[0,1] op_sel_hi:[1,0]
	v_pk_add_f32 v[50:51], v[50:51], v[50:51] op_sel:[0,1] op_sel_hi:[1,0]
	v_mov_b32_e32 v43, v89
	v_mov_b32_e32 v51, v88
	v_pk_add_f32 v[42:43], v[50:51], v[42:43]
	s_nop 0
	v_pk_add_f32 v[42:43], v[42:43], v[62:63]
	s_nop 0
	v_add_f32_e32 v32, v42, v43
	ds_bpermute_b32 v42, v33, v32
	s_waitcnt lgkmcnt(0)
	v_add_f32_e32 v32, v32, v42
	ds_bpermute_b32 v42, v34, v32
	s_waitcnt lgkmcnt(0)
	v_add_f32_e32 v32, v32, v42
	ds_bpermute_b32 v42, v35, v32
	s_waitcnt lgkmcnt(0)
	v_add_f32_e32 v32, v32, v42
	ds_bpermute_b32 v42, v36, v32
	s_waitcnt lgkmcnt(0)
	v_add_f32_e32 v32, v32, v42
	ds_bpermute_b32 v42, v37, v32
	s_waitcnt lgkmcnt(0)
	v_add_f32_e32 v32, v32, v42
	ds_bpermute_b32 v42, v38, v32
	s_waitcnt lgkmcnt(0)
	v_add_f32_e32 v32, v32, v42
	v_fmamk_f32 v32, v32, 0x3a000000, v39
	v_mul_f32_e32 v42, 0x4f800000, v32
	v_cmp_gt_f32_e32 vcc, s12, v32
	s_nop 1
	v_cndmask_b32_e32 v32, v32, v42, vcc
	v_sqrt_f32_e32 v42, v32
	s_nop 0
	v_add_u32_e32 v43, -1, v42
	v_add_u32_e32 v50, 1, v42
	v_fma_f32 v51, -v43, v42, v32
	v_fma_f32 v62, -v50, v42, v32
	v_cmp_ge_f32_e64 s[0:1], 0, v51
	s_nop 1
	v_cndmask_b32_e64 v42, v42, v43, s[0:1]
	v_cmp_lt_f32_e64 s[0:1], 0, v62
	s_nop 1
	v_cndmask_b32_e64 v42, v42, v50, s[0:1]
	v_mul_f32_e32 v43, 0x37800000, v42
	v_cndmask_b32_e32 v42, v42, v43, vcc
	v_cmp_class_f32_e32 vcc, v32, v40
	s_nop 1
	v_cndmask_b32_e32 v32, v42, v32, vcc
	v_div_scale_f32 v42, s[0:1], v32, v32, 1.0
	v_rcp_f32_e32 v50, v42
	v_div_scale_f32 v43, vcc, 1.0, v32, 1.0
	v_fma_f32 v51, -v42, v50, 1.0
	v_fmac_f32_e32 v50, v51, v50
	v_mul_f32_e32 v51, v43, v50
	v_fma_f32 v62, -v42, v51, v43
	v_fmac_f32_e32 v51, v62, v50
	v_fma_f32 v42, -v42, v51, v43
	v_div_fmas_f32 v42, v42, v50, v51
	v_div_fixup_f32 v32, v42, v32, 1.0
	v_pk_mul_f32 v[48:49], v[32:33], v[48:49] op_sel_hi:[0,1]
	v_pk_mul_f32 v[42:43], v[32:33], v[64:65] op_sel_hi:[0,1]
	v_pk_mul_f32 v[44:45], v[48:49], v[44:45]
	v_pk_mul_f32 v[42:43], v[42:43], v[68:69]
	v_and_b32_sdwa v50, v45, v41 dst_sel:DWORD dst_unused:UNUSED_PAD src0_sel:WORD_1 src1_sel:DWORD
	v_and_b32_sdwa v51, v44, v41 dst_sel:DWORD dst_unused:UNUSED_PAD src0_sel:WORD_1 src1_sel:DWORD
	v_and_b32_sdwa v48, v43, v41 dst_sel:DWORD dst_unused:UNUSED_PAD src0_sel:WORD_1 src1_sel:DWORD
	v_and_b32_sdwa v49, v42, v41 dst_sel:DWORD dst_unused:UNUSED_PAD src0_sel:WORD_1 src1_sel:DWORD
	v_add3_u32 v45, v45, v50, s13
	v_add3_u32 v44, v44, v51, s13
	v_add3_u32 v42, v42, v49, s13
	v_add3_u32 v43, v43, v48, s13
	v_and_b32_e32 v45, 0xffff0000, v45
	v_and_b32_e32 v44, 0xffff0000, v44
	v_or_b32_sdwa v43, v45, v43 dst_sel:DWORD dst_unused:UNUSED_PAD src0_sel:DWORD src1_sel:WORD_1
	v_or_b32_sdwa v42, v44, v42 dst_sel:DWORD dst_unused:UNUSED_PAD src0_sel:DWORD src1_sel:WORD_1
	flat_store_dwordx2 v[28:29], v[42:43]
	v_pk_mul_f32 v[48:49], v[32:33], v[52:53] op_sel_hi:[0,1]
	v_pk_mul_f32 v[46:47], v[32:33], v[46:47] op_sel_hi:[0,1]
	v_mov_b64_e32 v[42:43], v[144:145]
	v_mov_b64_e32 v[44:45], v[146:147]
	v_mov_b32_e32 v51, v44
	v_mov_b32_e32 v44, v43
	v_mov_b32_e32 v50, v42
	v_pk_mul_f32 v[44:45], v[48:49], v[44:45]
	v_pk_mul_f32 v[42:43], v[46:47], v[50:51]
	v_and_b32_sdwa v48, v45, v41 dst_sel:DWORD dst_unused:UNUSED_PAD src0_sel:WORD_1 src1_sel:DWORD
	v_and_b32_sdwa v49, v44, v41 dst_sel:DWORD dst_unused:UNUSED_PAD src0_sel:WORD_1 src1_sel:DWORD
	v_and_b32_sdwa v46, v43, v41 dst_sel:DWORD dst_unused:UNUSED_PAD src0_sel:WORD_1 src1_sel:DWORD
	v_and_b32_sdwa v47, v42, v41 dst_sel:DWORD dst_unused:UNUSED_PAD src0_sel:WORD_1 src1_sel:DWORD
	v_add3_u32 v45, v45, v48, s13
	v_add3_u32 v44, v44, v49, s13
	v_add3_u32 v42, v42, v47, s13
	v_add3_u32 v43, v43, v46, s13
	v_and_b32_e32 v45, 0xffff0000, v45
	v_and_b32_e32 v44, 0xffff0000, v44
	v_or_b32_sdwa v43, v45, v43 dst_sel:DWORD dst_unused:UNUSED_PAD src0_sel:DWORD src1_sel:WORD_1
	v_or_b32_sdwa v42, v44, v42 dst_sel:DWORD dst_unused:UNUSED_PAD src0_sel:DWORD src1_sel:WORD_1
	flat_store_dwordx2 v[28:29], v[42:43] offset:512
	v_mov_b32_e32 v47, v56
	v_mov_b32_e32 v56, v55
	v_mov_b32_e32 v46, v54
	v_pk_mul_f32 v[48:49], v[32:33], v[56:57] op_sel_hi:[0,1]
	v_pk_mul_f32 v[46:47], v[32:33], v[46:47] op_sel_hi:[0,1]
	v_mov_b64_e32 v[42:43], v[148:149]
	v_mov_b64_e32 v[44:45], v[150:151]
	v_mov_b32_e32 v51, v44
	v_mov_b32_e32 v44, v43
	v_mov_b32_e32 v50, v42
	v_pk_mul_f32 v[44:45], v[48:49], v[44:45]
	v_pk_mul_f32 v[42:43], v[46:47], v[50:51]
	v_and_b32_sdwa v48, v45, v41 dst_sel:DWORD dst_unused:UNUSED_PAD src0_sel:WORD_1 src1_sel:DWORD
	v_and_b32_sdwa v49, v44, v41 dst_sel:DWORD dst_unused:UNUSED_PAD src0_sel:WORD_1 src1_sel:DWORD
	v_and_b32_sdwa v46, v43, v41 dst_sel:DWORD dst_unused:UNUSED_PAD src0_sel:WORD_1 src1_sel:DWORD
	v_and_b32_sdwa v47, v42, v41 dst_sel:DWORD dst_unused:UNUSED_PAD src0_sel:WORD_1 src1_sel:DWORD
	v_add3_u32 v45, v45, v48, s13
	v_add3_u32 v44, v44, v49, s13
	v_add3_u32 v42, v42, v47, s13
	v_add3_u32 v43, v43, v46, s13
	v_and_b32_e32 v45, 0xffff0000, v45
	v_and_b32_e32 v44, 0xffff0000, v44
	v_or_b32_sdwa v43, v45, v43 dst_sel:DWORD dst_unused:UNUSED_PAD src0_sel:DWORD src1_sel:WORD_1
	v_or_b32_sdwa v42, v44, v42 dst_sel:DWORD dst_unused:UNUSED_PAD src0_sel:DWORD src1_sel:WORD_1
	flat_store_dwordx2 v[28:29], v[42:43] offset:1024
	v_mov_b32_e32 v47, v60
	v_mov_b32_e32 v60, v59
	v_mov_b32_e32 v46, v58
	v_pk_mul_f32 v[48:49], v[32:33], v[60:61] op_sel_hi:[0,1]
	v_pk_mul_f32 v[46:47], v[32:33], v[46:47] op_sel_hi:[0,1]
	v_mov_b64_e32 v[42:43], v[152:153]
	v_mov_b64_e32 v[44:45], v[154:155]
	v_mov_b32_e32 v51, v44
	v_mov_b32_e32 v44, v43
	v_mov_b32_e32 v50, v42
	v_pk_mul_f32 v[44:45], v[48:49], v[44:45]
	v_pk_mul_f32 v[42:43], v[46:47], v[50:51]
	v_and_b32_sdwa v48, v45, v41 dst_sel:DWORD dst_unused:UNUSED_PAD src0_sel:WORD_1 src1_sel:DWORD
	v_and_b32_sdwa v49, v44, v41 dst_sel:DWORD dst_unused:UNUSED_PAD src0_sel:WORD_1 src1_sel:DWORD
	v_and_b32_sdwa v46, v43, v41 dst_sel:DWORD dst_unused:UNUSED_PAD src0_sel:WORD_1 src1_sel:DWORD
	v_and_b32_sdwa v47, v42, v41 dst_sel:DWORD dst_unused:UNUSED_PAD src0_sel:WORD_1 src1_sel:DWORD
	v_add3_u32 v45, v45, v48, s13
	v_add3_u32 v44, v44, v49, s13
	v_add3_u32 v42, v42, v47, s13
	v_add3_u32 v43, v43, v46, s13
	v_and_b32_e32 v45, 0xffff0000, v45
	v_and_b32_e32 v44, 0xffff0000, v44
	v_or_b32_sdwa v43, v45, v43 dst_sel:DWORD dst_unused:UNUSED_PAD src0_sel:DWORD src1_sel:WORD_1
	v_or_b32_sdwa v42, v44, v42 dst_sel:DWORD dst_unused:UNUSED_PAD src0_sel:DWORD src1_sel:WORD_1
	flat_store_dwordx2 v[28:29], v[42:43] offset:1536
	v_mov_b32_e32 v46, v14
	v_mov_b32_e32 v47, v16
	v_mov_b32_e32 v16, v15
	v_pk_mul_f32 v[14:15], v[32:33], v[46:47] op_sel_hi:[0,1]
	v_pk_mul_f32 v[16:17], v[32:33], v[16:17] op_sel_hi:[0,1]
	v_mov_b64_e32 v[42:43], v[156:157]
	v_mov_b64_e32 v[44:45], v[158:159]
	v_mov_b32_e32 v47, v44
	v_mov_b32_e32 v44, v43
	v_mov_b32_e32 v46, v42
	v_pk_mul_f32 v[16:17], v[16:17], v[44:45]
	v_pk_mul_f32 v[14:15], v[14:15], v[46:47]
	v_and_b32_sdwa v44, v17, v41 dst_sel:DWORD dst_unused:UNUSED_PAD src0_sel:WORD_1 src1_sel:DWORD
	v_and_b32_sdwa v45, v16, v41 dst_sel:DWORD dst_unused:UNUSED_PAD src0_sel:WORD_1 src1_sel:DWORD
	v_and_b32_sdwa v42, v15, v41 dst_sel:DWORD dst_unused:UNUSED_PAD src0_sel:WORD_1 src1_sel:DWORD
	v_and_b32_sdwa v43, v14, v41 dst_sel:DWORD dst_unused:UNUSED_PAD src0_sel:WORD_1 src1_sel:DWORD
	v_add3_u32 v17, v17, v44, s13
	v_add3_u32 v16, v16, v45, s13
	v_add3_u32 v14, v14, v43, s13
	v_add3_u32 v15, v15, v42, s13
	v_and_b32_e32 v17, 0xffff0000, v17
	v_and_b32_e32 v16, 0xffff0000, v16
	v_or_b32_sdwa v15, v17, v15 dst_sel:DWORD dst_unused:UNUSED_PAD src0_sel:DWORD src1_sel:WORD_1
	v_or_b32_sdwa v14, v16, v14 dst_sel:DWORD dst_unused:UNUSED_PAD src0_sel:DWORD src1_sel:WORD_1
	flat_store_dwordx2 v[28:29], v[14:15] offset:2048
	v_mov_b32_e32 v42, v10
	v_mov_b32_e32 v43, v12
	v_mov_b32_e32 v12, v11
	v_pk_mul_f32 v[10:11], v[32:33], v[42:43] op_sel_hi:[0,1]
	v_pk_mul_f32 v[12:13], v[32:33], v[12:13] op_sel_hi:[0,1]
	v_mov_b64_e32 v[14:15], v[160:161]
	v_mov_b64_e32 v[16:17], v[162:163]
	v_mov_b32_e32 v43, v16
	v_mov_b32_e32 v16, v15
	v_mov_b32_e32 v42, v14
	v_pk_mul_f32 v[12:13], v[12:13], v[16:17]
	v_pk_mul_f32 v[10:11], v[10:11], v[42:43]
	v_and_b32_sdwa v16, v13, v41 dst_sel:DWORD dst_unused:UNUSED_PAD src0_sel:WORD_1 src1_sel:DWORD
	v_and_b32_sdwa v17, v12, v41 dst_sel:DWORD dst_unused:UNUSED_PAD src0_sel:WORD_1 src1_sel:DWORD
	v_and_b32_sdwa v14, v11, v41 dst_sel:DWORD dst_unused:UNUSED_PAD src0_sel:WORD_1 src1_sel:DWORD
	v_and_b32_sdwa v15, v10, v41 dst_sel:DWORD dst_unused:UNUSED_PAD src0_sel:WORD_1 src1_sel:DWORD
	v_add3_u32 v13, v13, v16, s13
	v_add3_u32 v12, v12, v17, s13
	v_add3_u32 v10, v10, v15, s13
	v_add3_u32 v11, v11, v14, s13
	v_and_b32_e32 v13, 0xffff0000, v13
	v_and_b32_e32 v12, 0xffff0000, v12
	v_or_b32_sdwa v11, v13, v11 dst_sel:DWORD dst_unused:UNUSED_PAD src0_sel:DWORD src1_sel:WORD_1
	v_or_b32_sdwa v10, v12, v10 dst_sel:DWORD dst_unused:UNUSED_PAD src0_sel:DWORD src1_sel:WORD_1
	flat_store_dwordx2 v[28:29], v[10:11] offset:2560
	v_mov_b32_e32 v14, v6
	v_mov_b32_e32 v15, v8
	v_mov_b32_e32 v8, v7
	v_pk_mul_f32 v[6:7], v[32:33], v[14:15] op_sel_hi:[0,1]
	v_pk_mul_f32 v[8:9], v[32:33], v[8:9] op_sel_hi:[0,1]
	v_mov_b64_e32 v[10:11], v[164:165]
	v_mov_b64_e32 v[12:13], v[166:167]
	v_mov_b32_e32 v15, v12
	v_mov_b32_e32 v12, v11
	v_mov_b32_e32 v14, v10
	v_pk_mul_f32 v[8:9], v[8:9], v[12:13]
	v_pk_mul_f32 v[6:7], v[6:7], v[14:15]
	v_and_b32_sdwa v12, v9, v41 dst_sel:DWORD dst_unused:UNUSED_PAD src0_sel:WORD_1 src1_sel:DWORD
	v_and_b32_sdwa v13, v8, v41 dst_sel:DWORD dst_unused:UNUSED_PAD src0_sel:WORD_1 src1_sel:DWORD
	v_and_b32_sdwa v10, v7, v41 dst_sel:DWORD dst_unused:UNUSED_PAD src0_sel:WORD_1 src1_sel:DWORD
	v_and_b32_sdwa v11, v6, v41 dst_sel:DWORD dst_unused:UNUSED_PAD src0_sel:WORD_1 src1_sel:DWORD
	v_add3_u32 v9, v9, v12, s13
	v_add3_u32 v8, v8, v13, s13
	v_add3_u32 v6, v6, v11, s13
	v_add3_u32 v7, v7, v10, s13
	v_and_b32_e32 v9, 0xffff0000, v9
	v_and_b32_e32 v8, 0xffff0000, v8
	v_or_b32_sdwa v7, v9, v7 dst_sel:DWORD dst_unused:UNUSED_PAD src0_sel:DWORD src1_sel:WORD_1
	v_or_b32_sdwa v6, v8, v6 dst_sel:DWORD dst_unused:UNUSED_PAD src0_sel:DWORD src1_sel:WORD_1
	flat_store_dwordx2 v[28:29], v[6:7] offset:3072
	v_mov_b32_e32 v10, v2
	v_mov_b32_e32 v11, v4
	v_mov_b32_e32 v4, v3
	v_pk_mul_f32 v[2:3], v[32:33], v[10:11] op_sel_hi:[0,1]
	v_pk_mul_f32 v[4:5], v[32:33], v[4:5] op_sel_hi:[0,1]
	v_mov_b64_e32 v[6:7], v[168:169]
	v_mov_b64_e32 v[8:9], v[170:171]
	v_mov_b32_e32 v11, v8
	v_mov_b32_e32 v8, v7
	v_mov_b32_e32 v10, v6
	v_pk_mul_f32 v[4:5], v[4:5], v[8:9]
	v_pk_mul_f32 v[2:3], v[2:3], v[10:11]
	v_and_b32_sdwa v8, v5, v41 dst_sel:DWORD dst_unused:UNUSED_PAD src0_sel:WORD_1 src1_sel:DWORD
	v_and_b32_sdwa v9, v4, v41 dst_sel:DWORD dst_unused:UNUSED_PAD src0_sel:WORD_1 src1_sel:DWORD
	v_and_b32_sdwa v6, v3, v41 dst_sel:DWORD dst_unused:UNUSED_PAD src0_sel:WORD_1 src1_sel:DWORD
	v_and_b32_sdwa v7, v2, v41 dst_sel:DWORD dst_unused:UNUSED_PAD src0_sel:WORD_1 src1_sel:DWORD
	v_add3_u32 v5, v5, v8, s13
	v_add3_u32 v4, v4, v9, s13
	v_add3_u32 v2, v2, v7, s13
	v_add3_u32 v3, v3, v6, s13
	v_and_b32_e32 v5, 0xffff0000, v5
	v_and_b32_e32 v4, 0xffff0000, v4
	v_or_b32_sdwa v3, v5, v3 dst_sel:DWORD dst_unused:UNUSED_PAD src0_sel:DWORD src1_sel:WORD_1
	v_or_b32_sdwa v2, v4, v2 dst_sel:DWORD dst_unused:UNUSED_PAD src0_sel:DWORD src1_sel:WORD_1
	flat_store_dwordx2 v[28:29], v[2:3] offset:3584
	v_lshl_add_u64 v[28:29], v[28:29], 0, s[6:7]
	s_cbranch_scc0 .LBB0_85
